# early L1 invalidate in XCD-local barriers; B12 made XCD-local with a split-phase completion check; leader releases before its own invalidate
# speedup vs baseline: 1.0315x; 1.0099x over previous
.LBB0_157:
	s_or_b64 exec, exec, s[6:7]
	s_mov_b64 s[6:7], exec
	v_mbcnt_lo_u32_b32 v0, s6, 0
	v_mbcnt_hi_u32_b32 v0, s7, v0
	v_cmp_eq_u32_e32 vcc, 0, v0
	s_waitcnt vmcnt(0)
	s_and_saveexec_b64 s[8:9], vcc
	s_cbranch_execz .LBB0_159
	s_bcnt1_i32_b64 s6, s[6:7]
	v_mov_b32_e32 v0, 0x2000
	v_mov_b32_e32 v1, s6
	global_atomic_add v0, v1, s[4:5] offset:1024
	buffer_inv sc1

.LBB0_233:
	s_or_b64 exec, exec, s[6:7]
	s_mov_b64 s[6:7], exec
	v_mbcnt_lo_u32_b32 v0, s6, 0
	v_mbcnt_hi_u32_b32 v0, s7, v0
	v_cmp_eq_u32_e32 vcc, 0, v0
	s_waitcnt vmcnt(0)
	s_and_saveexec_b64 s[8:9], vcc
	s_cbranch_execz .LBB0_235
	s_bcnt1_i32_b64 s3, s[6:7]
	v_mov_b32_e32 v0, 0x2000
	v_mov_b32_e32 v1, s3
	global_atomic_add v0, v1, s[4:5] offset:1024
	buffer_inv sc1

.LBB0_268:
	s_mov_b64 s[6:7], exec
	s_lshl_b32 s3, s96, 8
	v_mbcnt_lo_u32_b32 v1, s6, 0
	s_add_u32 s4, s94, s3
	v_mbcnt_hi_u32_b32 v1, s7, v1
	s_addc_u32 s5, s95, 0
	v_cmp_eq_u32_e32 vcc, 0, v1
	s_and_saveexec_b64 s[8:9], vcc
	s_cbranch_execz .LBB0_270
	s_bcnt1_i32_b64 s3, s[6:7]
	v_mov_b32_e32 v3, 0x1000
	v_mov_b32_e32 v4, s3
	global_atomic_add v3, v3, v4, s[4:5] offset:1024 sc0
	s_cmp_lg_u32 s98, 0
	s_cbranch_scc0 .Lei_2
	buffer_inv sc1
.Lei_2:
.LBB0_270:
	s_or_b64 exec, exec, s[8:9]
	v_cvt_f32_u32_e32 v4, v2
	s_cmp_lg_u32 s98, 0
	s_cbranch_scc1 .Lw1_2
	s_waitcnt vmcnt(0)
	s_branch .Lw2_2
.Lw1_2:
	s_waitcnt vmcnt(1)
.Lw2_2:
	v_readfirstlane_b32 s3, v3
	v_sub_u32_e32 v3, 0, v2
	v_rcp_iflag_f32_e32 v4, v4
	v_add_u32_e32 v5, s3, v1
	v_mul_f32_e32 v4, 0x4f7ffffe, v4
	v_cvt_u32_f32_e32 v4, v4
	v_mul_lo_u32 v1, v3, v4
	v_mul_hi_u32 v1, v4, v1
	v_add_u32_e32 v1, v4, v1
	v_mul_hi_u32 v1, v5, v1
	v_mul_lo_u32 v3, v1, v2
	v_sub_u32_e32 v3, v5, v3
	v_add_u32_e32 v4, 1, v1
	v_cmp_ge_u32_e32 vcc, v3, v2
	s_nop 1
	v_cndmask_b32_e32 v1, v1, v4, vcc
	v_sub_u32_e32 v4, v3, v2
	v_cndmask_b32_e32 v3, v3, v4, vcc
	v_add_u32_e32 v4, 1, v1
	v_cmp_ge_u32_e32 vcc, v3, v2
	v_add_u32_e32 v3, 1, v5
	s_nop 0
	v_cndmask_b32_e32 v1, v1, v4, vcc
	v_mul_lo_u32 v4, v2, v1
	v_add_u32_e32 v2, v4, v2
	v_cmp_ne_u32_e32 vcc, v3, v2
	s_and_saveexec_b64 s[6:7], vcc
	s_xor_b64 s[6:7], exec, s[6:7]
	s_cbranch_execz .LBB0_284
	s_waitcnt lgkmcnt(0)
	v_mov_b32_e32 v0, 0x2000
	global_load_dword v0, v0, s[4:5] offset:1024 sc1
	s_add_u32 s14, s4, 0x2400
	s_addc_u32 s15, s5, 0
	s_waitcnt vmcnt(0)
	v_cmp_eq_u32_e32 vcc, v0, v1
	s_and_saveexec_b64 s[8:9], vcc
	s_cbranch_execz .LBB0_283
	s_add_u32 s10, s72, 0x5c0200
	s_addc_u32 s11, s73, 0
	s_mov_b32 s3, 1
	s_mov_b64 s[18:19], 0
	v_mov_b32_e32 v0, 0
	s_branch .LBB0_274

.LBB0_283:
	s_or_b64 exec, exec, s[8:9]
	s_waitcnt vmcnt(0)
	s_cmp_lg_u32 s98, 0
	s_cbranch_scc1 .Lsk1_2
	buffer_inv sc1
.Lsk1_2:
	s_waitcnt vmcnt(0)
.LBB0_284:
	s_andn2_saveexec_b64 s[6:7], s[6:7]
	s_cbranch_execz .LBB0_304
	s_mov_b64 s[6:7], exec
	s_cmp_lg_u32 s98, 0
	s_cbranch_scc1 .LBB0_301
	buffer_wbl2 sc1
	s_waitcnt lgkmcnt(0)
	s_waitcnt vmcnt(0)
	v_mbcnt_lo_u32_b32 v1, s6, 0
	v_mbcnt_hi_u32_b32 v1, s7, v1
	v_cmp_eq_u32_e32 vcc, 0, v1
	s_and_saveexec_b64 s[8:9], vcc
	s_cbranch_execz .LBB0_287
	s_bcnt1_i32_b64 s3, s[6:7]
	v_mov_b32_e32 v2, 0x5c3000
	v_mov_b32_e32 v3, s3
	global_atomic_add v2, v2, v3, s[72:73] offset:1024 sc0

.LBB0_301:
	s_or_b64 exec, exec, s[6:7]
	s_mov_b64 s[6:7], exec
	v_mbcnt_lo_u32_b32 v0, s6, 0
	v_mbcnt_hi_u32_b32 v0, s7, v0
	v_cmp_eq_u32_e32 vcc, 0, v0
	s_cmp_lg_u32 s98, 0
	s_cbranch_scc1 .Lsk3_2
	s_waitcnt vmcnt(0)
.Lsk3_2:
	s_and_saveexec_b64 s[8:9], vcc
	s_cbranch_execz .LBB0_303
	s_bcnt1_i32_b64 s3, s[6:7]
	v_mov_b32_e32 v0, 0x2000
	v_mov_b32_e32 v1, s3
	global_atomic_add v0, v1, s[4:5] offset:1024
	s_cmp_lg_u32 s98, 0
	s_cbranch_scc1 .Lsk2_2
	buffer_inv sc1
.Lsk2_2:
.LBB0_303:
	s_or_b64 exec, exec, s[8:9]
	s_waitcnt vmcnt(0)

.Lsk1_3:
	s_waitcnt vmcnt(0)
.LBB0_364:
	s_andn2_saveexec_b64 s[6:7], s[6:7]
	s_cbranch_execz .LBB0_384
	s_mov_b64 s[6:7], exec
	s_cmp_lg_u32 s98, 0
	s_cbranch_scc1 .LBB0_381
	buffer_wbl2 sc1
	s_waitcnt lgkmcnt(0)
	s_waitcnt vmcnt(0)
	v_mbcnt_lo_u32_b32 v1, s6, 0
	v_mbcnt_hi_u32_b32 v1, s7, v1
	v_cmp_eq_u32_e32 vcc, 0, v1
	s_and_saveexec_b64 s[8:9], vcc
	s_cbranch_execz .LBB0_367
	s_bcnt1_i32_b64 s3, s[6:7]
	v_mov_b32_e32 v2, 0x5c3000
	v_mov_b32_e32 v3, s3
	global_atomic_add v2, v2, v3, s[72:73] offset:1024 sc0

.LBB0_925:
	s_or_b64 exec, exec, s[10:11]
	s_mov_b64 s[10:11], exec
	v_mbcnt_lo_u32_b32 v0, s10, 0
	v_mbcnt_hi_u32_b32 v0, s11, v0
	v_cmp_eq_u32_e32 vcc, 0, v0
	s_waitcnt vmcnt(0)
	s_and_saveexec_b64 s[14:15], vcc
	s_cbranch_execz .LBB0_927
	s_bcnt1_i32_b64 s10, s[10:11]
	v_mov_b32_e32 v0, 0x2000
	v_mov_b32_e32 v1, s10
	global_atomic_add v0, v1, s[6:7] offset:1024
	buffer_inv sc1

.LBB0_1009:
	s_or_b64 exec, exec, s[10:11]
	s_mov_b64 s[10:11], exec
	v_mbcnt_lo_u32_b32 v0, s10, 0
	v_mbcnt_hi_u32_b32 v0, s11, v0
	v_cmp_eq_u32_e32 vcc, 0, v0
	s_waitcnt vmcnt(0)
	s_and_saveexec_b64 s[14:15], vcc
	s_cbranch_execz .LBB0_1011
	s_bcnt1_i32_b64 s3, s[10:11]
	v_mov_b32_e32 v0, 0x2000
	v_mov_b32_e32 v1, s3
	global_atomic_add v0, v1, s[4:5] offset:1024
	buffer_inv sc1

.LBB0_1052:
	s_mov_b64 s[10:11], exec
	s_lshl_b32 s3, s96, 8
	v_mbcnt_lo_u32_b32 v1, s10, 0
	s_add_u32 s4, s94, s3
	v_mbcnt_hi_u32_b32 v1, s11, v1
	s_addc_u32 s5, s95, 0
	v_cmp_eq_u32_e32 vcc, 0, v1
	s_and_saveexec_b64 s[14:15], vcc
	s_cbranch_execz .LBB0_1054
	s_bcnt1_i32_b64 s3, s[10:11]
	v_mov_b32_e32 v3, 0x1000
	v_mov_b32_e32 v4, s3
	global_atomic_add v3, v3, v4, s[4:5] offset:1024 sc0
	s_cmp_lg_u32 s98, 0
	s_cbranch_scc0 .Lei_8
	buffer_inv sc1
.Lei_8:
.LBB0_1054:
	s_or_b64 exec, exec, s[14:15]
	v_cvt_f32_u32_e32 v4, v2
	s_cmp_lg_u32 s98, 0
	s_cbranch_scc1 .Lw1_8
	s_waitcnt vmcnt(0)
	s_branch .Lw2_8

.Lw2_8:
	v_readfirstlane_b32 s3, v3
	v_sub_u32_e32 v3, 0, v2
	v_rcp_iflag_f32_e32 v4, v4
	v_add_u32_e32 v5, s3, v1
	v_mul_f32_e32 v4, 0x4f7ffffe, v4
	v_cvt_u32_f32_e32 v4, v4
	v_mul_lo_u32 v1, v3, v4
	v_mul_hi_u32 v1, v4, v1
	v_add_u32_e32 v1, v4, v1
	v_mul_hi_u32 v1, v5, v1
	v_mul_lo_u32 v3, v1, v2
	v_sub_u32_e32 v3, v5, v3
	v_add_u32_e32 v4, 1, v1
	v_cmp_ge_u32_e32 vcc, v3, v2
	s_nop 1
	v_cndmask_b32_e32 v1, v1, v4, vcc
	v_sub_u32_e32 v4, v3, v2
	v_cndmask_b32_e32 v3, v3, v4, vcc
	v_add_u32_e32 v4, 1, v1
	v_cmp_ge_u32_e32 vcc, v3, v2
	v_add_u32_e32 v3, 1, v5
	s_nop 0
	v_cndmask_b32_e32 v1, v1, v4, vcc
	v_mul_lo_u32 v4, v2, v1
	v_add_u32_e32 v2, v4, v2
	v_cmp_ne_u32_e32 vcc, v3, v2
	s_and_saveexec_b64 s[10:11], vcc
	s_xor_b64 s[10:11], exec, s[10:11]
	s_cbranch_execz .LBB0_1068
	s_waitcnt lgkmcnt(0)
	v_mov_b32_e32 v0, 0x2000
	global_load_dword v0, v0, s[4:5] offset:1024 sc1
	s_add_u32 s18, s4, 0x2400
	s_addc_u32 s19, s5, 0
	s_waitcnt vmcnt(0)
	v_cmp_eq_u32_e32 vcc, v0, v1
	s_and_saveexec_b64 s[14:15], vcc
	s_cbranch_execz .LBB0_1067
	s_add_u32 s16, s72, 0x5c0200
	s_addc_u32 s17, s73, 0
	s_mov_b32 s3, 1
	s_mov_b64 s[36:37], 0
	v_mov_b32_e32 v0, 0
	s_branch .LBB0_1058

.LBB0_1067:
	s_or_b64 exec, exec, s[14:15]
	s_waitcnt vmcnt(0)
	s_cmp_lg_u32 s98, 0
	s_cbranch_scc1 .Lsk1_8
	buffer_inv sc1
.Lsk1_8:
	s_waitcnt vmcnt(0)
.LBB0_1068:
	s_andn2_saveexec_b64 s[10:11], s[10:11]
	s_cbranch_execz .LBB0_1088
	s_mov_b64 s[10:11], exec
	s_cmp_lg_u32 s98, 0
	s_cbranch_scc1 .LBB0_1085
	buffer_wbl2 sc1
	s_waitcnt lgkmcnt(0)
	s_waitcnt vmcnt(0)
	v_mbcnt_lo_u32_b32 v1, s10, 0
	v_mbcnt_hi_u32_b32 v1, s11, v1
	v_cmp_eq_u32_e32 vcc, 0, v1
	s_and_saveexec_b64 s[14:15], vcc
	s_cbranch_execz .LBB0_1071
	s_bcnt1_i32_b64 s3, s[10:11]
	v_mov_b32_e32 v2, 0x5c3000
	v_mov_b32_e32 v3, s3
	global_atomic_add v2, v2, v3, s[72:73] offset:1024 sc0

.LBB0_1085:
	s_or_b64 exec, exec, s[10:11]
	s_mov_b64 s[10:11], exec
	v_mbcnt_lo_u32_b32 v0, s10, 0
	v_mbcnt_hi_u32_b32 v0, s11, v0
	v_cmp_eq_u32_e32 vcc, 0, v0
	s_cmp_lg_u32 s98, 0
	s_cbranch_scc1 .Lsk3_8
	s_waitcnt vmcnt(0)
.Lsk3_8:
	s_and_saveexec_b64 s[14:15], vcc
	s_cbranch_execz .LBB0_1087
	s_bcnt1_i32_b64 s3, s[10:11]
	v_mov_b32_e32 v0, 0x2000
	v_mov_b32_e32 v1, s3
	global_atomic_add v0, v1, s[4:5] offset:1024
	s_cmp_lg_u32 s98, 0
	s_cbranch_scc1 .Lsk2_8
	buffer_inv sc1
.Lsk2_8:
.LBB0_1087:
	s_or_b64 exec, exec, s[14:15]
	s_waitcnt vmcnt(0)

.LBB0_1128:
	s_mov_b64 s[8:9], exec
	s_lshl_b32 s3, s96, 8
	v_mbcnt_lo_u32_b32 v1, s8, 0
	s_add_u32 s4, s94, s3
	v_mbcnt_hi_u32_b32 v1, s9, v1
	s_addc_u32 s5, s95, 0
	v_cmp_eq_u32_e32 vcc, 0, v1
	s_and_saveexec_b64 s[10:11], vcc
	s_cbranch_execz .LBB0_1130
	s_bcnt1_i32_b64 s3, s[8:9]
	v_mov_b32_e32 v3, 0x1000
	v_mov_b32_e32 v4, s3
	global_atomic_add v3, v3, v4, s[4:5] offset:1024 sc0
	s_cmp_lg_u32 s98, 0
	s_cbranch_scc0 .Lei_9
	buffer_inv sc1
.Lei_9:
.LBB0_1130:
	s_or_b64 exec, exec, s[10:11]
	v_cvt_f32_u32_e32 v4, v2
	s_cmp_lg_u32 s98, 0
	s_cbranch_scc1 .Lw1_9
	s_waitcnt vmcnt(0)
	s_branch .Lw2_9

.Lw2_9:
	v_readfirstlane_b32 s3, v3
	v_sub_u32_e32 v3, 0, v2
	v_rcp_iflag_f32_e32 v4, v4
	v_add_u32_e32 v5, s3, v1
	v_mul_f32_e32 v4, 0x4f7ffffe, v4
	v_cvt_u32_f32_e32 v4, v4
	v_mul_lo_u32 v1, v3, v4
	v_mul_hi_u32 v1, v4, v1
	v_add_u32_e32 v1, v4, v1
	v_mul_hi_u32 v1, v5, v1
	v_mul_lo_u32 v3, v1, v2
	v_sub_u32_e32 v3, v5, v3
	v_add_u32_e32 v4, 1, v1
	v_cmp_ge_u32_e32 vcc, v3, v2
	s_nop 1
	v_cndmask_b32_e32 v1, v1, v4, vcc
	v_sub_u32_e32 v4, v3, v2
	v_cndmask_b32_e32 v3, v3, v4, vcc
	v_add_u32_e32 v4, 1, v1
	v_cmp_ge_u32_e32 vcc, v3, v2
	v_add_u32_e32 v3, 1, v5
	s_nop 0
	v_cndmask_b32_e32 v1, v1, v4, vcc
	v_mul_lo_u32 v4, v2, v1
	v_add_u32_e32 v2, v4, v2
	v_cmp_ne_u32_e32 vcc, v3, v2
	s_and_saveexec_b64 s[8:9], vcc
	s_xor_b64 s[8:9], exec, s[8:9]
	s_cbranch_execz .LBB0_1144
	s_waitcnt lgkmcnt(0)
	v_mov_b32_e32 v0, 0x2000
	global_load_dword v0, v0, s[4:5] offset:1024 sc1
	s_add_u32 s16, s4, 0x2400
	s_addc_u32 s17, s5, 0
	s_waitcnt vmcnt(0)
	v_cmp_eq_u32_e32 vcc, v0, v1
	s_and_saveexec_b64 s[10:11], vcc
	s_cbranch_execz .LBB0_1143
	s_add_u32 s14, s72, 0x5c0200
	s_addc_u32 s15, s73, 0
	s_mov_b32 s3, 1
	s_mov_b64 s[18:19], 0
	v_mov_b32_e32 v0, 0
	s_branch .LBB0_1134

.LBB0_1143:
	s_or_b64 exec, exec, s[10:11]
	s_waitcnt vmcnt(0)
	s_cmp_lg_u32 s98, 0
	s_cbranch_scc1 .Lsk1_9
	buffer_inv sc1
.Lsk1_9:
	s_waitcnt vmcnt(0)
.LBB0_1144:
	s_andn2_saveexec_b64 s[8:9], s[8:9]
	s_cbranch_execz .LBB0_1164
	s_mov_b64 s[8:9], exec
	s_cmp_lg_u32 s98, 0
	s_cbranch_scc1 .LBB0_1161
	buffer_wbl2 sc1
	s_waitcnt lgkmcnt(0)
	s_waitcnt vmcnt(0)
	v_mbcnt_lo_u32_b32 v1, s8, 0
	v_mbcnt_hi_u32_b32 v1, s9, v1
	v_cmp_eq_u32_e32 vcc, 0, v1
	s_and_saveexec_b64 s[10:11], vcc
	s_cbranch_execz .LBB0_1147
	s_bcnt1_i32_b64 s3, s[8:9]
	v_mov_b32_e32 v2, 0x5c3000
	v_mov_b32_e32 v3, s3
	global_atomic_add v2, v2, v3, s[72:73] offset:1024 sc0

.LBB0_1161:
	s_or_b64 exec, exec, s[8:9]
	s_mov_b64 s[8:9], exec
	v_mbcnt_lo_u32_b32 v0, s8, 0
	v_mbcnt_hi_u32_b32 v0, s9, v0
	v_cmp_eq_u32_e32 vcc, 0, v0
	s_cmp_lg_u32 s98, 0
	s_cbranch_scc1 .Lsk3_9
	s_waitcnt vmcnt(0)
.Lsk3_9:
	s_and_saveexec_b64 s[10:11], vcc
	s_cbranch_execz .LBB0_1163
	s_bcnt1_i32_b64 s3, s[8:9]
	v_mov_b32_e32 v0, 0x2000
	v_mov_b32_e32 v1, s3
	global_atomic_add v0, v1, s[4:5] offset:1024
	v_mov_b32_e32 v0, 0x3640
	global_atomic_add v0, v1, s[94:95]
	s_cmp_lg_u32 s98, 0
	s_cbranch_scc1 .Lsk2_9
	buffer_inv sc1
.Lsk2_9:
.LBB0_1163:
	s_or_b64 exec, exec, s[10:11]
	s_waitcnt vmcnt(0)

.Lsk1_10:
	s_waitcnt vmcnt(0)
.LBB0_1220:
	s_andn2_saveexec_b64 s[8:9], s[8:9]
	s_cbranch_execz .LBB0_1240
	s_mov_b64 s[8:9], exec
	s_cmp_lg_u32 s98, 0
	s_cbranch_scc1 .LBB0_1237
	buffer_wbl2 sc1
	s_waitcnt lgkmcnt(0)
	s_waitcnt vmcnt(0)
	v_mbcnt_lo_u32_b32 v1, s8, 0
	v_mbcnt_hi_u32_b32 v1, s9, v1
	v_cmp_eq_u32_e32 vcc, 0, v1
	s_and_saveexec_b64 s[10:11], vcc
	s_cbranch_execz .LBB0_1223
	s_bcnt1_i32_b64 s3, s[8:9]
	v_mov_b32_e32 v2, 0x5c3000
	v_mov_b32_e32 v3, s3
	global_atomic_add v2, v2, v3, s[72:73] offset:1024 sc0

.Lsk3_10:
	s_and_saveexec_b64 s[10:11], vcc
	s_cbranch_execz .LBB0_1239
	s_bcnt1_i32_b64 s3, s[8:9]
	v_mov_b32_e32 v0, 0x2000
	v_mov_b32_e32 v1, s3
	global_atomic_add v0, v1, s[4:5] offset:1024
	s_cmp_lg_u32 s98, 0
	s_cbranch_scc1 .Lsk2_10
	buffer_inv sc1

.LBB0_1279:
	s_andn2_saveexec_b64 s[8:9], s[8:9]
	s_cbranch_execz .LBB0_1299
	s_mov_b64 s[8:9], exec
	s_cmp_lg_u32 s98, 0
	s_cbranch_scc0 .Lb12_full
.Lb12_spin:
	v_mov_b32_e32 v2, 0x3640
	global_load_dword v3, v2, s[94:95] sc1
	s_waitcnt vmcnt(0)
	v_cmp_ge_u32_e32 vcc, v3, v0
	s_cbranch_vccnz .LBB0_1296
	s_sleep 1
	s_branch .Lb12_spin
.Lb12_full:
	buffer_wbl2 sc1
	s_waitcnt lgkmcnt(0)
	s_waitcnt vmcnt(0)
	v_mbcnt_lo_u32_b32 v1, s8, 0
	v_mbcnt_hi_u32_b32 v1, s9, v1
	v_cmp_eq_u32_e32 vcc, 0, v1
	s_and_saveexec_b64 s[10:11], vcc
	s_cbranch_execz .LBB0_1282
	s_bcnt1_i32_b64 s3, s[8:9]
	v_mov_b32_e32 v2, 0x5c3000
	v_mov_b32_e32 v3, s3
	global_atomic_add v2, v2, v3, s[72:73] offset:1024 sc0

.Lsk1_12:
	s_waitcnt vmcnt(0)
.LBB0_1347:
	s_andn2_saveexec_b64 s[8:9], s[8:9]
	s_cbranch_execz .LBB0_1367
	s_mov_b64 s[8:9], exec
	s_cmp_lg_u32 s98, 0
	s_cbranch_scc1 .LBB0_1364
	buffer_wbl2 sc1
	s_waitcnt lgkmcnt(0)
	s_waitcnt vmcnt(0)
	v_mbcnt_lo_u32_b32 v1, s8, 0
	v_mbcnt_hi_u32_b32 v1, s9, v1
	v_cmp_eq_u32_e32 vcc, 0, v1
	s_and_saveexec_b64 s[10:11], vcc
	s_cbranch_execz .LBB0_1350
	s_bcnt1_i32_b64 s3, s[8:9]
	v_mov_b32_e32 v2, 0x5c3000
	v_mov_b32_e32 v3, s3
	global_atomic_add v2, v2, v3, s[72:73] offset:1024 sc0

.LBB0_1411:
	s_mov_b64 s[4:5], exec
	s_lshl_b32 s2, s96, 8
	v_mbcnt_lo_u32_b32 v1, s4, 0
	s_add_u32 s2, s94, s2
	v_mbcnt_hi_u32_b32 v1, s5, v1
	s_addc_u32 s3, s95, 0
	v_cmp_eq_u32_e32 vcc, 0, v1
	s_and_saveexec_b64 s[6:7], vcc
	s_cbranch_execz .LBB0_1413
	s_bcnt1_i32_b64 s4, s[4:5]
	v_mov_b32_e32 v3, 0x1000
	v_mov_b32_e32 v4, s4
	global_atomic_add v3, v3, v4, s[2:3] offset:1024 sc0
	s_cmp_lg_u32 s98, 0
	s_cbranch_scc0 .Lei_13
	buffer_inv sc1
.Lei_13:
.LBB0_1413:
	s_or_b64 exec, exec, s[6:7]
	v_cvt_f32_u32_e32 v4, v2
	s_cmp_lg_u32 s98, 0
	s_cbranch_scc1 .Lw1_13
	s_waitcnt vmcnt(0)
	s_branch .Lw2_13

.Lw2_13:
	v_readfirstlane_b32 s4, v3
	v_sub_u32_e32 v3, 0, v2
	v_rcp_iflag_f32_e32 v4, v4
	v_add_u32_e32 v5, s4, v1
	v_mul_f32_e32 v4, 0x4f7ffffe, v4
	v_cvt_u32_f32_e32 v4, v4
	v_mul_lo_u32 v1, v3, v4
	v_mul_hi_u32 v1, v4, v1
	v_add_u32_e32 v1, v4, v1
	v_mul_hi_u32 v1, v5, v1
	v_mul_lo_u32 v3, v1, v2
	v_sub_u32_e32 v3, v5, v3
	v_add_u32_e32 v4, 1, v1
	v_cmp_ge_u32_e32 vcc, v3, v2
	s_nop 1
	v_cndmask_b32_e32 v1, v1, v4, vcc
	v_sub_u32_e32 v4, v3, v2
	v_cndmask_b32_e32 v3, v3, v4, vcc
	v_add_u32_e32 v4, 1, v1
	v_cmp_ge_u32_e32 vcc, v3, v2
	v_add_u32_e32 v3, 1, v5
	s_nop 0
	v_cndmask_b32_e32 v1, v1, v4, vcc
	v_mul_lo_u32 v4, v2, v1
	v_add_u32_e32 v2, v4, v2
	v_cmp_ne_u32_e32 vcc, v3, v2
	s_and_saveexec_b64 s[4:5], vcc
	s_xor_b64 s[4:5], exec, s[4:5]
	s_cbranch_execz .LBB0_1427
	s_waitcnt lgkmcnt(0)
	v_mov_b32_e32 v0, 0x2000
	global_load_dword v0, v0, s[2:3] offset:1024 sc1
	s_add_u32 s10, s2, 0x2400
	s_addc_u32 s11, s3, 0
	s_waitcnt vmcnt(0)
	v_cmp_eq_u32_e32 vcc, v0, v1
	s_and_saveexec_b64 s[6:7], vcc
	s_cbranch_execz .LBB0_1426
	s_add_u32 s8, s72, 0x5c0200
	s_addc_u32 s9, s73, 0
	s_mov_b32 s24, 1
	s_mov_b64 s[12:13], 0
	v_mov_b32_e32 v0, 0
	s_branch .LBB0_1417

.LBB0_1426:
	s_or_b64 exec, exec, s[6:7]
	s_waitcnt vmcnt(0)
	s_cmp_lg_u32 s98, 0
	s_cbranch_scc1 .Lsk1_13
	buffer_inv sc1
.Lsk1_13:
	s_waitcnt vmcnt(0)
.LBB0_1427:
	s_andn2_saveexec_b64 s[4:5], s[4:5]
	s_cbranch_execz .LBB0_1447
	s_mov_b64 s[4:5], exec
	s_cmp_lg_u32 s98, 0
	s_cbranch_scc1 .LBB0_1444
	buffer_wbl2 sc1
	s_waitcnt lgkmcnt(0)
	s_waitcnt vmcnt(0)
	v_mbcnt_lo_u32_b32 v1, s4, 0
	v_mbcnt_hi_u32_b32 v1, s5, v1
	v_cmp_eq_u32_e32 vcc, 0, v1
	s_and_saveexec_b64 s[6:7], vcc
	s_cbranch_execz .LBB0_1430
	s_bcnt1_i32_b64 s4, s[4:5]
	v_mov_b32_e32 v2, 0x5c3000
	v_mov_b32_e32 v3, s4
	global_atomic_add v2, v2, v3, s[72:73] offset:1024 sc0

.LBB0_1444:
	s_or_b64 exec, exec, s[4:5]
	s_mov_b64 s[4:5], exec
	v_mbcnt_lo_u32_b32 v0, s4, 0
	v_mbcnt_hi_u32_b32 v0, s5, v0
	v_cmp_eq_u32_e32 vcc, 0, v0
	s_cmp_lg_u32 s98, 0
	s_cbranch_scc1 .Lsk3_13
	s_waitcnt vmcnt(0)
.Lsk3_13:
	s_and_saveexec_b64 s[6:7], vcc
	s_cbranch_execz .LBB0_1446
	s_bcnt1_i32_b64 s4, s[4:5]
	v_mov_b32_e32 v0, 0x2000
	v_mov_b32_e32 v1, s4
	global_atomic_add v0, v1, s[2:3] offset:1024
	s_cmp_lg_u32 s98, 0
	s_cbranch_scc1 .Lsk2_13
	buffer_inv sc1
.Lsk2_13:
.LBB0_1446:
	s_or_b64 exec, exec, s[6:7]
	s_waitcnt vmcnt(0)
